# phase-0 compression-constant dot products: 32 iterations of loads in flight instead of one (same fmac order)
# speedup vs baseline: 1.0127x; 1.0127x over previous
; DI float* F32L(const Params& p, int l) { return (float*)(PWS(p) + WS_F32) + (size_t)l * F32_PER_LAYER; }
; DI void phase0(const Params& p, char* smem) {
;     ...
;     const int e = tid & 63, part = tid >> 6;
;     float a = 0.f;
;     for (int i = part * 256; i < part * 256 + 256; ++i) a += pe[i] * wc[(size_t)i * 64 + e];
;     __syncthreads();
;     red[part * 64 + e] = a;
;     __syncthreads();
;     if (tid < 64) {
;       float s = 0.f;
;       for (int q = 0; q < 8; ++q) s += red[q * 64 + tid];
;       F32L(p, l)[(kv ? F_CV : F_CK) + tid] = s;
;     }
.LBB0_1149:
	s_mov_b64 s[10:11], 0x1000
	v_lshl_add_u64 v[164:165], v[10:11], 0, s[10:11]
	global_load_dword v100, v[8:9], off
	global_load_dword v132, v[10:11], off
	global_load_dword v101, v[8:9], off offset:4
	global_load_dword v133, v[10:11], off offset:256
	global_load_dword v102, v[8:9], off offset:8
	global_load_dword v134, v[10:11], off offset:512
	global_load_dword v103, v[8:9], off offset:12
	global_load_dword v135, v[10:11], off offset:768
	global_load_dword v104, v[8:9], off offset:16
	global_load_dword v136, v[10:11], off offset:1024
	global_load_dword v105, v[8:9], off offset:20
	global_load_dword v137, v[10:11], off offset:1280
	global_load_dword v106, v[8:9], off offset:24
	global_load_dword v138, v[10:11], off offset:1536
	global_load_dword v107, v[8:9], off offset:28
	global_load_dword v139, v[10:11], off offset:1792
	global_load_dword v108, v[8:9], off offset:32
	global_load_dword v140, v[10:11], off offset:2048
	global_load_dword v109, v[8:9], off offset:36
	global_load_dword v141, v[10:11], off offset:2304
	global_load_dword v110, v[8:9], off offset:40
	global_load_dword v142, v[10:11], off offset:2560
	global_load_dword v111, v[8:9], off offset:44
	global_load_dword v143, v[10:11], off offset:2816
	global_load_dword v112, v[8:9], off offset:48
	global_load_dword v144, v[10:11], off offset:3072
	global_load_dword v113, v[8:9], off offset:52
	global_load_dword v145, v[10:11], off offset:3328
	global_load_dword v114, v[8:9], off offset:56
	global_load_dword v146, v[10:11], off offset:3584
	global_load_dword v115, v[8:9], off offset:60
	global_load_dword v147, v[10:11], off offset:3840
	global_load_dword v116, v[8:9], off offset:64
	global_load_dword v148, v[164:165], off
	global_load_dword v117, v[8:9], off offset:68
	global_load_dword v149, v[164:165], off offset:256
	global_load_dword v118, v[8:9], off offset:72
	global_load_dword v150, v[164:165], off offset:512
	global_load_dword v119, v[8:9], off offset:76
	global_load_dword v151, v[164:165], off offset:768
	global_load_dword v120, v[8:9], off offset:80
	global_load_dword v152, v[164:165], off offset:1024
	global_load_dword v121, v[8:9], off offset:84
	global_load_dword v153, v[164:165], off offset:1280
	global_load_dword v122, v[8:9], off offset:88
	global_load_dword v154, v[164:165], off offset:1536
	global_load_dword v123, v[8:9], off offset:92
	global_load_dword v155, v[164:165], off offset:1792
	global_load_dword v124, v[8:9], off offset:96
	global_load_dword v156, v[164:165], off offset:2048
	global_load_dword v125, v[8:9], off offset:100
	global_load_dword v157, v[164:165], off offset:2304
	global_load_dword v126, v[8:9], off offset:104
	global_load_dword v158, v[164:165], off offset:2560
	global_load_dword v127, v[8:9], off offset:108
	global_load_dword v159, v[164:165], off offset:2816
	global_load_dword v128, v[8:9], off offset:112
	global_load_dword v160, v[164:165], off offset:3072
	global_load_dword v129, v[8:9], off offset:116
	global_load_dword v161, v[164:165], off offset:3328
	global_load_dword v130, v[8:9], off offset:120
	global_load_dword v162, v[164:165], off offset:3584
	global_load_dword v131, v[8:9], off offset:124
	global_load_dword v163, v[164:165], off offset:3840
	v_add_u32_e32 v15, 32, v15
	v_cmp_ge_i32_e32 vcc, v15, v12
	s_mov_b64 s[10:11], 0x80
	v_lshl_add_u64 v[8:9], v[8:9], 0, s[10:11]
	s_mov_b64 s[10:11], 0x2000
	v_lshl_add_u64 v[10:11], v[10:11], 0, s[10:11]
	s_or_b64 s[4:5], vcc, s[4:5]
	s_waitcnt vmcnt(0)
	v_fmac_f32_e32 v14, v100, v132
	v_fmac_f32_e32 v14, v101, v133
	v_fmac_f32_e32 v14, v102, v134
	v_fmac_f32_e32 v14, v103, v135
	v_fmac_f32_e32 v14, v104, v136
	v_fmac_f32_e32 v14, v105, v137
	v_fmac_f32_e32 v14, v106, v138
	v_fmac_f32_e32 v14, v107, v139
	v_fmac_f32_e32 v14, v108, v140
	v_fmac_f32_e32 v14, v109, v141
	v_fmac_f32_e32 v14, v110, v142
	v_fmac_f32_e32 v14, v111, v143
	v_fmac_f32_e32 v14, v112, v144
	v_fmac_f32_e32 v14, v113, v145
	v_fmac_f32_e32 v14, v114, v146
	v_fmac_f32_e32 v14, v115, v147
	v_fmac_f32_e32 v14, v116, v148
	v_fmac_f32_e32 v14, v117, v149
	v_fmac_f32_e32 v14, v118, v150
	v_fmac_f32_e32 v14, v119, v151
	v_fmac_f32_e32 v14, v120, v152
	v_fmac_f32_e32 v14, v121, v153
	v_fmac_f32_e32 v14, v122, v154
	v_fmac_f32_e32 v14, v123, v155
	v_fmac_f32_e32 v14, v124, v156
	v_fmac_f32_e32 v14, v125, v157
	v_fmac_f32_e32 v14, v126, v158
	v_fmac_f32_e32 v14, v127, v159
	v_fmac_f32_e32 v14, v128, v160
	v_fmac_f32_e32 v14, v129, v161
	v_fmac_f32_e32 v14, v130, v162
	v_fmac_f32_e32 v14, v131, v163
	s_andn2_b64 exec, exec, s[4:5]
	s_cbranch_execnz .LBB0_1149
	s_or_b64 exec, exec, s[4:5]
	s_barrier
	ds_write_b32 v0, v14
	s_waitcnt lgkmcnt(0)
	s_barrier
	s_and_saveexec_b64 s[4:5], s[8:9]
	s_cbranch_execz .LBB0_1147
	ds_read2st64_b32 v[8:9], v0 offset1:1
	ds_read2st64_b32 v[10:11], v0 offset0:2 offset1:3
	ds_read2st64_b32 v[14:15], v0 offset0:4 offset1:5
	ds_read2st64_b32 v[16:17], v0 offset0:6 offset1:7
	v_readlane_b32 s12, v254, 33
	s_waitcnt lgkmcnt(3)
	v_add_f32_e32 v8, 0, v8
	v_add_f32_e32 v8, v8, v9
	v_readlane_b32 s14, v254, 35
	v_readlane_b32 s15, v254, 36
	v_mov_b32 v18, s14
	v_mov_b32 v19, s15
	s_mul_hi_i32 s11, s0, 0x8600
	v_readfirstlane_b32 s1, v18
	s_mul_i32 s0, s0, 0x8600
	s_waitcnt lgkmcnt(2)
	v_add_f32_e32 v8, v8, v10
	v_readfirstlane_b32 s10, v19
	s_add_u32 s0, s1, s0
	v_add_f32_e32 v8, v8, v11
	s_addc_u32 s1, s10, s11
	s_waitcnt lgkmcnt(1)
	v_add_f32_e32 v8, v8, v14
	s_cmp_eq_u32 s7, 0
	v_add_f32_e32 v8, v8, v15
	s_movk_i32 s7, 0x2100
	s_waitcnt lgkmcnt(0)
	v_add_f32_e32 v8, v8, v16
	s_cselect_b32 s7, s7, 0x2140
	v_add_f32_e32 v10, v8, v17
	v_add_u32_e32 v8, s7, v34
	v_ashrrev_i32_e32 v9, 31, v8
	v_lshl_add_u64 v[8:9], v[8:9], 2, s[0:1]
	v_add_co_u32_e32 v8, vcc, 0x7980000, v8
	v_readlane_b32 s13, v254, 34
	s_nop 0
	v_addc_co_u32_e32 v9, vcc, 0, v9, vcc
	global_store_dword v[8:9], v10, off
	s_branch .LBB0_1147
